# LRG: LRU pass-A gates section hand-written (8 MFMAs up front, 4-way interleaved chains, exact sqrt fix-up kept, unreachable denormal rescale dropped)
# speedup vs baseline: 1.0100x; 1.0091x over previous
; #define LAS __attribute__((address_space(3)))
; __device__ __forceinline__ float fast_sigmoid(float z) { return __builtin_amdgcn_rcpf(1.f + __builtin_amdgcn_exp2f(-z * L2E)); }
; __device__ __forceinline__ void lru_item(const Args& a, LAS unsigned char* lds, const int s, const int seg, const int hb, const int tid_in, const int lane_in, const int wave) {
;     ...
; #pragma unroll
;         for (int mi = 0; mi < 2; ++mi) { const int mt = mt0 + mi; f32x4 pr = {0.f, 0.f, 0.f, 0.f}, pi = {0.f, 0.f, 0.f, 0.f};
; #pragma unroll
;             for (int ks = 0; ks < 2; ++ks) { const bf16x8 af = *(const LAS bf16x8*)(xcb + (mt * 16 + fr) * 72 + ks * 32 + fq * 8);
;                 pr = __builtin_amdgcn_mfma_f32_16x16x32_bf16(af, brg[ks], pr, 0, 0, 0); pi = __builtin_amdgcn_mfma_f32_16x16x32_bf16(af, big[ks], pi, 0, 0, 0); }
; #pragma unroll
;             for (int i = 0; i < 4; ++i) { const int t = mt * 16 + 4 * fq + i;
;                 const float r = fast_sigmoid(pr[i] + e_brg), ig = fast_sigmoid(pi[i] + e_big);
;                 const float av = __builtin_amdgcn_exp2f(r * e_ls);
;                 float mult = sqrtf(fmaxf(1.f - av * av, 0.f));
;                 if (!fin && tb + k * 64 + t == 0) mult = 1.f;
;                 const float xcv = xcf[t * 68 + jt * 16 + fr];
;                 LA[t * 64 + jt * 16 + fr] = av; LB[t * 64 + jt * 16 + fr] = mult * ig * xcv; } }
.LBB0_565:
	ds_read_b128 v[86:89], v120
	ds_read_b128 v[90:93], v120 offset:64
	ds_read_b128 v[160:163], v122
	ds_read_b128 v[164:167], v122 offset:64
	ds_read_b32 v172, v121 offset:9216
	ds_read_b32 v173, v121 offset:9488
	ds_read_b32 v174, v121 offset:9760
	ds_read_b32 v175, v121 offset:10032
	ds_read_b32 v176, v123 offset:9216
	ds_read_b32 v177, v123 offset:9488
	ds_read_b32 v178, v123 offset:9760
	ds_read_b32 v179, v123 offset:10032
	s_waitcnt lgkmcnt(11)
	v_mfma_f32_16x16x32_bf16 v[94:97], v[86:89], v[44:47], 0
	s_waitcnt lgkmcnt(9)
	v_mfma_f32_16x16x32_bf16 v[168:171], v[160:163], v[44:47], 0
	v_mfma_f32_16x16x32_bf16 v[94:97], v[90:93], v[52:55], v[94:97]
	s_waitcnt lgkmcnt(8)
	v_mfma_f32_16x16x32_bf16 v[168:171], v[164:167], v[52:55], v[168:171]
	v_mfma_f32_16x16x32_bf16 v[86:89], v[86:89], v[48:51], 0
	v_mfma_f32_16x16x32_bf16 v[160:163], v[160:163], v[48:51], 0
	v_mfma_f32_16x16x32_bf16 v[86:89], v[90:93], v[56:59], v[86:89]
	v_mfma_f32_16x16x32_bf16 v[160:163], v[164:167], v[56:59], v[160:163]
	s_nop 7
	v_add_f32_e32 v94, v102, v94
	v_add_f32_e32 v95, v102, v95
	v_add_f32_e32 v96, v102, v96
	v_add_f32_e32 v97, v102, v97
	v_mul_f32_e32 v94, 0xbfb8aa3b, v94
	v_mul_f32_e32 v95, 0xbfb8aa3b, v95
	v_mul_f32_e32 v96, 0xbfb8aa3b, v96
	v_mul_f32_e32 v97, 0xbfb8aa3b, v97
	v_exp_f32_e32 v94, v94
	v_exp_f32_e32 v95, v95
	v_exp_f32_e32 v96, v96
	v_exp_f32_e32 v97, v97
	v_add_f32_e32 v86, v103, v86
	v_add_f32_e32 v87, v103, v87
	v_add_f32_e32 v88, v103, v88
	v_add_f32_e32 v89, v103, v89
	v_add_f32_e32 v94, 1.0, v94
	v_add_f32_e32 v95, 1.0, v95
	v_add_f32_e32 v96, 1.0, v96
	v_add_f32_e32 v97, 1.0, v97
	v_mul_f32_e32 v86, 0xbfb8aa3b, v86
	v_mul_f32_e32 v87, 0xbfb8aa3b, v87
	v_mul_f32_e32 v88, 0xbfb8aa3b, v88
	v_mul_f32_e32 v89, 0xbfb8aa3b, v89
	v_rcp_f32_e32 v94, v94
	v_rcp_f32_e32 v95, v95
	v_rcp_f32_e32 v96, v96
	v_rcp_f32_e32 v97, v97
	v_exp_f32_e32 v86, v86
	v_exp_f32_e32 v87, v87
	v_exp_f32_e32 v88, v88
	v_exp_f32_e32 v89, v89
	v_mul_f32_e32 v94, v105, v94
	v_mul_f32_e32 v95, v105, v95
	v_mul_f32_e32 v96, v105, v96
	v_mul_f32_e32 v97, v105, v97
	v_exp_f32_e32 v94, v94
	v_exp_f32_e32 v95, v95
	v_exp_f32_e32 v96, v96
	v_exp_f32_e32 v97, v97
	v_add_f32_e32 v86, 1.0, v86
	v_add_f32_e32 v87, 1.0, v87
	v_add_f32_e32 v88, 1.0, v88
	v_add_f32_e32 v89, 1.0, v89
	v_rcp_f32_e32 v86, v86
	v_rcp_f32_e32 v87, v87
	v_rcp_f32_e32 v88, v88
	v_rcp_f32_e32 v89, v89
	v_fma_f32 v180, -v94, v94, 1.0
	v_fma_f32 v181, -v95, v95, 1.0
	v_fma_f32 v182, -v96, v96, 1.0
	v_fma_f32 v183, -v97, v97, 1.0
	v_max_f32_e32 v180, 0, v180
	v_max_f32_e32 v181, 0, v181
	v_max_f32_e32 v182, 0, v182
	v_max_f32_e32 v183, 0, v183
	v_sqrt_f32_e32 v184, v180
	v_sqrt_f32_e32 v185, v181
	v_sqrt_f32_e32 v186, v182
	v_sqrt_f32_e32 v187, v183
	v_add_u32_e32 v188, -1, v184
	v_add_u32_e32 v189, -1, v185
	v_add_u32_e32 v190, -1, v186
	v_add_u32_e32 v191, -1, v187
	v_add_u32_e32 v98, 1, v184
	v_add_u32_e32 v99, 1, v185
	v_add_u32_e32 v100, 1, v186
	v_add_u32_e32 v101, 1, v187
	v_fma_f32 v1, -v188, v184, v180
	v_fma_f32 v2, -v189, v185, v181
	v_fma_f32 v3, -v190, v186, v182
	v_fma_f32 v126, -v191, v187, v183
	v_fma_f32 v180, -v98, v184, v180
	v_fma_f32 v181, -v99, v185, v181
	v_fma_f32 v182, -v100, v186, v182
	v_fma_f32 v183, -v101, v187, v183
	v_cmp_ge_f32_e64 vcc, 0, v1
	v_cmp_ge_f32_e64 s[0:1], 0, v2
	v_cmp_ge_f32_e64 s[82:83], 0, v3
	v_cndmask_b32_e64 v184, v184, v188, vcc
	v_cmp_ge_f32_e64 vcc, 0, v126
	v_cndmask_b32_e64 v185, v185, v189, s[0:1]
	v_cndmask_b32_e64 v186, v186, v190, s[82:83]
	v_cndmask_b32_e64 v187, v187, v191, vcc
	v_cmp_lt_f32_e64 s[0:1], 0, v180
	v_cmp_lt_f32_e64 s[82:83], 0, v181
	v_cmp_lt_f32_e64 vcc, 0, v182
	v_cndmask_b32_e64 v184, v184, v98, s[0:1]
	v_cmp_lt_f32_e64 s[0:1], 0, v183
	v_cndmask_b32_e64 v185, v185, v99, s[82:83]
	v_cndmask_b32_e64 v186, v186, v100, vcc
	v_cmp_ne_u32_e32 vcc, v116, v104
	v_cndmask_b32_e64 v187, v187, v101, s[0:1]
	v_mul_f32_e32 v87, v87, v185
	v_mul_f32_e32 v88, v88, v186
	v_cndmask_b32_e32 v184, 1.0, v184, vcc
	v_mul_f32_e32 v89, v89, v187
	s_waitcnt lgkmcnt(4)
; #define LAS __attribute__((address_space(3)))
; __device__ __forceinline__ float fast_sigmoid(float z) { return __builtin_amdgcn_rcpf(1.f + __builtin_amdgcn_exp2f(-z * L2E)); }
; __device__ __forceinline__ void lru_item(const Args& a, LAS unsigned char* lds, const int s, const int seg, const int hb, const int tid_in, const int lane_in, const int wave) {
;     ...
; #pragma unroll
;         for (int mi = 0; mi < 2; ++mi) { const int mt = mt0 + mi; f32x4 pr = {0.f, 0.f, 0.f, 0.f}, pi = {0.f, 0.f, 0.f, 0.f};
; #pragma unroll
;             for (int ks = 0; ks < 2; ++ks) { const bf16x8 af = *(const LAS bf16x8*)(xcb + (mt * 16 + fr) * 72 + ks * 32 + fq * 8);
;                 pr = __builtin_amdgcn_mfma_f32_16x16x32_bf16(af, brg[ks], pr, 0, 0, 0); pi = __builtin_amdgcn_mfma_f32_16x16x32_bf16(af, big[ks], pi, 0, 0, 0); }
; #pragma unroll
;             for (int i = 0; i < 4; ++i) { const int t = mt * 16 + 4 * fq + i;
;                 const float r = fast_sigmoid(pr[i] + e_brg), ig = fast_sigmoid(pi[i] + e_big);
;                 const float av = __builtin_amdgcn_exp2f(r * e_ls);
;                 float mult = sqrtf(fmaxf(1.f - av * av, 0.f));
;                 if (!fin && tb + k * 64 + t == 0) mult = 1.f;
;                 const float xcv = xcf[t * 68 + jt * 16 + fr];
;                 LA[t * 64 + jt * 16 + fr] = av; LB[t * 64 + jt * 16 + fr] = mult * ig * xcv; } }
;         __syncthreads();
;         float av[8], bv[8];
;         { float Ap = 1.f, Bp = 0.f;
; #pragma unroll
;           for (int i = 0; i < 8; ++i) { av[i] = LA[(sseg * 8 + i) * 64 + sj]; bv[i] = LB[(sseg * 8 + i) * 64 + sj]; Bp = av[i] * Bp + bv[i]; Ap *= av[i]; }
;           SA[sseg * 64 + sj] = Ap; SB[sseg * 64 + sj] = Bp; }
;         __syncthreads();
;         { float hv = HC[(k & 1) * 64 + sj], pv = PC[(k & 1) * 64 + sj];
; #pragma unroll
;           for (int q = 0; q < 8; ++q) { const float A_ = SA[q * 64 + sj], B_ = SB[q * 64 + sj]; if (q < sseg) { hv = A_ * hv + B_; pv *= A_; } }
	v_mul_f32_e32 v86, v86, v184
	v_mul_f32_e32 v87, v173, v87
	v_mul_f32_e32 v88, v174, v88
	v_mul_f32_e32 v89, v175, v89
	v_mul_f32_e32 v86, v172, v86
	ds_write2st64_b32 v108, v95, v87 offset0:104 offset1:168
	ds_write2st64_b32 v109, v96, v88 offset0:104 offset1:168
	ds_write2st64_b32 v110, v97, v89 offset0:104 offset1:168
	ds_write2st64_b32 v107, v94, v86 offset0:104 offset1:168
	v_add_f32_e32 v168, v102, v168
	v_add_f32_e32 v169, v102, v169
	v_add_f32_e32 v170, v102, v170
	v_add_f32_e32 v171, v102, v171
	v_mul_f32_e32 v168, 0xbfb8aa3b, v168
	v_mul_f32_e32 v169, 0xbfb8aa3b, v169
	v_mul_f32_e32 v170, 0xbfb8aa3b, v170
	v_mul_f32_e32 v171, 0xbfb8aa3b, v171
	v_exp_f32_e32 v168, v168
	v_exp_f32_e32 v169, v169
	v_exp_f32_e32 v170, v170
	v_exp_f32_e32 v171, v171
	v_add_f32_e32 v160, v103, v160
	v_add_f32_e32 v161, v103, v161
	v_add_f32_e32 v162, v103, v162
	v_add_f32_e32 v163, v103, v163
	v_add_f32_e32 v168, 1.0, v168
	v_add_f32_e32 v169, 1.0, v169
	v_add_f32_e32 v170, 1.0, v170
	v_add_f32_e32 v171, 1.0, v171
	v_mul_f32_e32 v160, 0xbfb8aa3b, v160
	v_mul_f32_e32 v161, 0xbfb8aa3b, v161
	v_mul_f32_e32 v162, 0xbfb8aa3b, v162
	v_mul_f32_e32 v163, 0xbfb8aa3b, v163
	v_rcp_f32_e32 v168, v168
	v_rcp_f32_e32 v169, v169
	v_rcp_f32_e32 v170, v170
	v_rcp_f32_e32 v171, v171
	v_exp_f32_e32 v160, v160
	v_exp_f32_e32 v161, v161
	v_exp_f32_e32 v162, v162
	v_exp_f32_e32 v163, v163
	v_mul_f32_e32 v168, v105, v168
	v_mul_f32_e32 v169, v105, v169
	v_mul_f32_e32 v170, v105, v170
	v_mul_f32_e32 v171, v105, v171
	v_exp_f32_e32 v168, v168
	v_exp_f32_e32 v169, v169
	v_exp_f32_e32 v170, v170
	v_exp_f32_e32 v171, v171
	v_add_f32_e32 v160, 1.0, v160
	v_add_f32_e32 v161, 1.0, v161
	v_add_f32_e32 v162, 1.0, v162
	v_add_f32_e32 v163, 1.0, v163
	v_rcp_f32_e32 v160, v160
	v_rcp_f32_e32 v161, v161
	v_rcp_f32_e32 v162, v162
	v_rcp_f32_e32 v163, v163
	v_fma_f32 v180, -v168, v168, 1.0
	v_fma_f32 v181, -v169, v169, 1.0
	v_fma_f32 v182, -v170, v170, 1.0
	v_fma_f32 v183, -v171, v171, 1.0
	v_max_f32_e32 v180, 0, v180
	v_max_f32_e32 v181, 0, v181
	v_max_f32_e32 v182, 0, v182
	v_max_f32_e32 v183, 0, v183
	v_sqrt_f32_e32 v184, v180
	v_sqrt_f32_e32 v185, v181
	v_sqrt_f32_e32 v186, v182
	v_sqrt_f32_e32 v187, v183
	v_add_u32_e32 v188, -1, v184
	v_add_u32_e32 v189, -1, v185
	v_add_u32_e32 v190, -1, v186
	v_add_u32_e32 v191, -1, v187
	v_add_u32_e32 v98, 1, v184
	v_add_u32_e32 v99, 1, v185
	v_add_u32_e32 v100, 1, v186
	v_add_u32_e32 v101, 1, v187
	v_fma_f32 v1, -v188, v184, v180
	v_fma_f32 v2, -v189, v185, v181
	v_fma_f32 v3, -v190, v186, v182
	v_fma_f32 v126, -v191, v187, v183
	v_fma_f32 v180, -v98, v184, v180
	v_fma_f32 v181, -v99, v185, v181
	v_fma_f32 v182, -v100, v186, v182
	v_fma_f32 v183, -v101, v187, v183
	v_cmp_ge_f32_e64 vcc, 0, v1
	v_cmp_ge_f32_e64 s[0:1], 0, v2
	v_cmp_ge_f32_e64 s[82:83], 0, v3
	v_cndmask_b32_e64 v184, v184, v188, vcc
	v_cmp_ge_f32_e64 vcc, 0, v126
	v_cndmask_b32_e64 v185, v185, v189, s[0:1]
	v_cndmask_b32_e64 v186, v186, v190, s[82:83]
	v_cndmask_b32_e64 v187, v187, v191, vcc
	v_cmp_lt_f32_e64 s[0:1], 0, v180
	v_cmp_lt_f32_e64 s[82:83], 0, v181
	v_cmp_lt_f32_e64 vcc, 0, v182
	v_cndmask_b32_e64 v184, v184, v98, s[0:1]
	v_cmp_lt_f32_e64 s[0:1], 0, v183
	v_cndmask_b32_e64 v185, v185, v99, s[82:83]
	v_cndmask_b32_e64 v186, v186, v100, vcc
	v_cmp_ne_u32_e32 vcc, v117, v104
	v_cndmask_b32_e64 v187, v187, v101, s[0:1]
	v_mul_f32_e32 v161, v161, v185
	v_mul_f32_e32 v162, v162, v186
	v_cndmask_b32_e32 v184, 1.0, v184, vcc
	v_mul_f32_e32 v163, v163, v187
	s_waitcnt lgkmcnt(0)
	v_mul_f32_e32 v160, v160, v184
	v_mul_f32_e32 v161, v177, v161
	v_mul_f32_e32 v162, v178, v162
	v_mul_f32_e32 v163, v179, v163
	v_mul_f32_e32 v160, v176, v160
	ds_write2st64_b32 v112, v169, v161 offset0:104 offset1:168
	ds_write2st64_b32 v113, v170, v162 offset0:104 offset1:168
	ds_write2st64_b32 v114, v171, v163 offset0:104 offset1:168
	ds_write2st64_b32 v111, v168, v160 offset0:104 offset1:168
	s_waitcnt lgkmcnt(0)
	s_barrier
	ds_read2st64_b32 v[96:97], v124 offset0:168 offset1:169
	ds_read2st64_b32 v[98:99], v124 offset0:104 offset1:105
	ds_read2st64_b32 v[92:93], v124 offset0:106 offset1:107
	ds_read2st64_b32 v[88:89], v124 offset0:108 offset1:109
	ds_read2st64_b32 v[86:87], v124 offset0:110 offset1:111
	ds_read2st64_b32 v[94:95], v124 offset0:170 offset1:171
	ds_read2st64_b32 v[90:91], v124 offset0:172 offset1:173
	ds_read2st64_b32 v[2:3], v124 offset0:174 offset1:175
	s_waitcnt lgkmcnt(6)
	v_fma_f32 v1, 0, v98, v96
	v_fma_f32 v1, v1, v99, v97
	v_mul_f32_e32 v100, v98, v99
	s_waitcnt lgkmcnt(2)
	v_fma_f32 v1, v1, v92, v94
	v_mul_f32_e32 v100, v100, v92
	v_fma_f32 v1, v1, v93, v95
	v_mul_f32_e32 v100, v100, v93
	s_waitcnt lgkmcnt(1)
	v_fma_f32 v1, v1, v88, v90
	v_mul_f32_e32 v100, v100, v88
	v_fma_f32 v1, v1, v89, v91
	v_mul_f32_e32 v100, v100, v89
	s_waitcnt lgkmcnt(0)
	v_fma_f32 v1, v1, v86, v2
	v_mul_f32_e32 v100, v100, v86
	v_fma_f32 v1, v1, v87, v3
	v_mul_f32_e32 v100, v100, v87
	ds_write2st64_b32 v125, v100, v1 offset0:232 offset1:240
	v_and_or_b32 v1, v104, 64, v77
	v_lshl_add_u32 v1, v1, 2, 0
	s_waitcnt lgkmcnt(0)
	s_barrier
	ds_read2st64_b32 v[100:101], v1 offset0:248 offset1:250
	s_and_saveexec_b64 s[0:1], s[4:5]
	s_cbranch_execnz .LBB0_577
	s_or_b64 exec, exec, s[0:1]
	s_and_saveexec_b64 s[0:1], s[6:7]
	s_cbranch_execnz .LBB0_578
